# P5 weight-transpose item: the 16 LDS reads of the transposition are issued in two batches with one wait each (were 16 serialized ds_read2 + lgkmcnt(0) round trips)
# baseline (speedup 1.0000x reference)
; #define LAS __attribute__((address_space(3)))
; __device__ __forceinline__ unsigned cvt_pk_bf16(float lo, float hi) { unsigned r; asm volatile("v_cvt_pk_bf16_f32 %0, %1, %2" : "=v"(r) : "v"(lo), "v"(hi)); return r; }
; #define LDS_WAIT() asm volatile("s_waitcnt lgkmcnt(0)" ::: "memory")
; __device__ __forceinline__ void tr_tile(const float* src, int ldw, const float* ksc, bf16_t* dst, int ldd, LAS float* scr, int lane) {
;     ...
;     LDS_WAIT();
;     const int c = lane & 7;
;     f32x4 k0 = (f32x4){1.f, 1.f, 1.f, 1.f}, k1 = k0;
;     if (ksc) { k0 = *(const f32x4*)(ksc + 8 * c); k1 = *(const f32x4*)(ksc + 8 * c + 4); }
; #pragma unroll
;     for (int j = 0; j < 4; ++j) { const int n = (lane >> 3) + 8 * j; const LAS float* s = scr + (8 * c) * 33 + n;
;         u32x4 o; o.x = cvt_pk_bf16(s[0 * 33] * k0[0], s[1 * 33] * k0[1]); o.y = cvt_pk_bf16(s[2 * 33] * k0[2], s[3 * 33] * k0[3]);
;         o.z = cvt_pk_bf16(s[4 * 33] * k1[0], s[5 * 33] * k1[1]); o.w = cvt_pk_bf16(s[6 * 33] * k1[2], s[7 * 33] * k1[3]);
;         *(u32x4*)(dst + (size_t)n * ldd + 8 * c) = o; }
;     LDS_WAIT();
.LBB0_855:
	ds_read2_b32 v[160:161], v11 offset1:33
	ds_read2_b32 v[162:163], v11 offset0:66 offset1:99
	ds_read2_b32 v[164:165], v11 offset0:132 offset1:165
	ds_read2_b32 v[166:167], v11 offset0:198 offset1:231
	ds_read2_b32 v[168:169], v11 offset0:8 offset1:41
	ds_read2_b32 v[170:171], v11 offset0:74 offset1:107
	ds_read2_b32 v[172:173], v11 offset0:140 offset1:173
	ds_read2_b32 v[174:175], v11 offset0:206 offset1:239
	s_ashr_i32 s7, s6, 31
	s_lshl_b64 s[6:7], s[6:7], 12
	s_add_u32 s6, s46, s6
	s_addc_u32 s7, s47, s7
	s_lshl_b64 s[4:5], s[4:5], 1
	s_add_u32 s4, s6, s4
	s_addc_u32 s5, s7, s5
	v_lshl_add_u64 v[98:99], s[4:5], 0, v[8:9]
	v_mov_b32_e32 v17, v9
	v_mov_b32_e32 v19, v9
	v_mov_b32_e32 v21, v9
	v_mov_b32_e32 v23, v9
	ds_read2_b32 v[176:177], v11 offset0:16 offset1:49
	ds_read2_b32 v[178:179], v11 offset0:82 offset1:115
	ds_read2_b32 v[180:181], v11 offset0:148 offset1:181
	ds_read2_b32 v[182:183], v11 offset0:214 offset1:247
	ds_read2_b32 v[184:185], v11 offset0:24 offset1:57
	ds_read2_b32 v[186:187], v11 offset0:90 offset1:123
	ds_read2_b32 v[188:189], v11 offset0:156 offset1:189
	ds_read2_b32 v[190:191], v11 offset0:222 offset1:255
	s_waitcnt vmcnt(0) lgkmcnt(8)
	v_mul_f32_e32 v200, v4, v160
	v_mul_f32_e32 v201, v5, v161
	v_cvt_pk_bf16_f32 v192, v200, v201
	v_mul_f32_e32 v200, v6, v162
	v_mul_f32_e32 v201, v7, v163
	v_cvt_pk_bf16_f32 v193, v200, v201
	v_mul_f32_e32 v200, v0, v164
	v_mul_f32_e32 v201, v1, v165
	v_cvt_pk_bf16_f32 v194, v200, v201
	v_mul_f32_e32 v200, v2, v166
	v_mul_f32_e32 v201, v3, v167
	v_cvt_pk_bf16_f32 v195, v200, v201
	v_lshl_add_u64 v[100:101], v[98:99], 0, v[16:17]
	global_store_dwordx4 v[100:101], v[192:195], off
	v_mul_f32_e32 v200, v4, v168
	v_mul_f32_e32 v201, v5, v169
	v_cvt_pk_bf16_f32 v196, v200, v201
	v_mul_f32_e32 v200, v6, v170
	v_mul_f32_e32 v201, v7, v171
	v_cvt_pk_bf16_f32 v197, v200, v201
	v_mul_f32_e32 v200, v0, v172
	v_mul_f32_e32 v201, v1, v173
	v_cvt_pk_bf16_f32 v198, v200, v201
	v_mul_f32_e32 v200, v2, v174
	v_mul_f32_e32 v201, v3, v175
	v_cvt_pk_bf16_f32 v199, v200, v201
	v_lshl_add_u64 v[100:101], v[98:99], 0, v[18:19]
	global_store_dwordx4 v[100:101], v[196:199], off
	s_waitcnt lgkmcnt(0)
	v_mul_f32_e32 v200, v4, v176
	v_mul_f32_e32 v201, v5, v177
	v_cvt_pk_bf16_f32 v192, v200, v201
	v_mul_f32_e32 v200, v6, v178
	v_mul_f32_e32 v201, v7, v179
	v_cvt_pk_bf16_f32 v193, v200, v201
	v_mul_f32_e32 v200, v0, v180
	v_mul_f32_e32 v201, v1, v181
	v_cvt_pk_bf16_f32 v194, v200, v201
	v_mul_f32_e32 v200, v2, v182
	v_mul_f32_e32 v201, v3, v183
	v_cvt_pk_bf16_f32 v195, v200, v201
	v_lshl_add_u64 v[100:101], v[98:99], 0, v[20:21]
	global_store_dwordx4 v[100:101], v[192:195], off
	v_mul_f32_e32 v200, v4, v184
	v_mul_f32_e32 v201, v5, v185
	v_cvt_pk_bf16_f32 v196, v200, v201
	v_mul_f32_e32 v200, v6, v186
	v_mul_f32_e32 v201, v7, v187
	v_cvt_pk_bf16_f32 v197, v200, v201
	v_mul_f32_e32 v200, v0, v188
	v_mul_f32_e32 v201, v1, v189
	v_cvt_pk_bf16_f32 v198, v200, v201
	v_mul_f32_e32 v200, v2, v190
	v_mul_f32_e32 v201, v3, v191
	v_cvt_pk_bf16_f32 v199, v200, v201
	v_lshl_add_u64 v[100:101], v[98:99], 0, v[22:23]
	global_store_dwordx4 v[100:101], v[196:199], off
	s_waitcnt lgkmcnt(0)
